# MLA rare rescale path moved out of line (common path falls through)
# speedup vs baseline: 1.0839x; 1.0011x over previous
; #define MFMA32(a, b, c) __builtin_amdgcn_mfma_f32_32x32x16_bf16((a), (b), (c), 0, 0, 0)
; DI float pl32_max(float v) { auto rr = __builtin_amdgcn_permlane32_swap(__float_as_uint(v), __float_as_uint(v), false, false); return fmaxf(__uint_as_float(rr[0]), __uint_as_float(rr[1])); }
; template <int OFF> DI s16x4 tr_read_o(unsigned addr) { s16x4 r; asm volatile("ds_read_b64_tr_b16 %0, %1 offset:%2" : "=&v"(r) : "v"(addr), "i"(OFF) : "memory"); return r; }
; DI float max_nn(float a, float b) { return __builtin_amdgcn_fmed3f(a, b, __builtin_inff()); }
; DI void mla_unit(const Params& p, char* lds, int seqbase, int S, int h, int qb) {
;     ...
;     const u16* kl = Kl + cur * 64 * KP + r32 * KP + 8 * hi;
;     f32x16 p0, p1;
;     { const bf16x8 k0 = *(const bf16x8*)(kl), k1 = *(const bf16x8*)(kl + 32 * KP);
;       p0 = MFMA32(k0, qf[0], negm); p1 = MFMA32(k1, qf[0], negm); }
; #pragma unroll
;     for (int d0 = 1; d0 < 6; ++d0) {
;       const bf16x8 k0 = *(const bf16x8*)(kl + d0 * 16), k1 = *(const bf16x8*)(kl + 32 * KP + d0 * 16);
;       p0 = MFMA32(k0, qf[d0], p0); p1 = MFMA32(k1, qf[d0], p1);
;     }
;     const unsigned tb = trb + cur * (64 * VP * 2);
;     constexpr int R8 = 8 * VP * 2;
;     const s16x4 a0 = tr_read_o<0>(tb), b0 = tr_read_o<R8>(tb), a1 = tr_read_o<2 * R8>(tb), b1 = tr_read_o<3 * R8>(tb);
;     const s16x4 a2 = tr_read_o<4 * R8>(tb), b2 = tr_read_o<5 * R8>(tb), a3 = tr_read_o<6 * R8>(tb), b3 = tr_read_o<7 * R8>(tb);
;     const s16x4 c0 = tr_read_o<64>(tb), d0_ = tr_read_o<R8 + 64>(tb), c1 = tr_read_o<2 * R8 + 64>(tb), d1 = tr_read_o<3 * R8 + 64>(tb);
;     const s16x4 c2 = tr_read_o<4 * R8 + 64>(tb), d2 = tr_read_o<5 * R8 + 64>(tb), c3 = tr_read_o<6 * R8 + 64>(tb), d3 = tr_read_o<7 * R8 + 64>(tb);
;     float pmax = max_nn(p0[0], p1[0]);
; #pragma unroll
;     for (int r = 1; r < 16; ++r) pmax = max_nn(pmax, max_nn(p0[r], p1[r]));
;     pmax = pl32_max(pmax);
;     if (kt == 0 || __any(pmax > 8.f)) {
;       const float delta = kt == 0 ? pmax : fmaxf(pmax, 0.f);
;       const float alpha = kt == 0 ? 1.f : __builtin_amdgcn_exp2f(-delta);
; #pragma unroll
;       for (int r = 0; r < 16; ++r) { negm[r] -= delta; p0[r] -= delta; p1[r] -= delta; o0[r] *= alpha; o1[r] *= alpha; }
;       l_run *= alpha;
;     }
.LBB0_1081:
	s_mul_i32 s28, s36, 0x3400
	v_add_u32_e32 v0, s28, v181
	ds_read_b128 v[2:5], v0
	ds_read_b128 v[6:9], v0 offset:32
	s_mul_i32 s28, s36, 0x3000
	s_cmp_eq_u32 s46, 0
	s_cselect_b64 s[50:51], -1, 0
	s_waitcnt lgkmcnt(1)
	v_mfma_f32_32x32x16_bf16 v[64:79], v[2:5], v[116:119], v[48:63]
	ds_read_b128 v[2:5], v0 offset:6656
	ds_read_b128 v[10:13], v0 offset:6688
	s_cmp_lg_u32 s46, 0
	s_waitcnt lgkmcnt(1)
	v_mfma_f32_32x32x16_bf16 v[80:95], v[2:5], v[116:119], v[48:63]
	v_mfma_f32_32x32x16_bf16 v[64:79], v[6:9], v[120:123], v[64:79]
	ds_read_b128 v[2:5], v0 offset:64
	ds_read_b128 v[6:9], v0 offset:96
	s_waitcnt lgkmcnt(2)
	v_mfma_f32_32x32x16_bf16 v[80:95], v[10:13], v[120:123], v[80:95]
	s_waitcnt lgkmcnt(1)
	v_mfma_f32_32x32x16_bf16 v[64:79], v[2:5], v[124:127], v[64:79]
	ds_read_b128 v[2:5], v0 offset:6720
	ds_read_b128 v[10:13], v0 offset:6752
	s_waitcnt lgkmcnt(1)
	v_mfma_f32_32x32x16_bf16 v[80:95], v[2:5], v[124:127], v[80:95]
	ds_read_b128 v[2:5], v0 offset:128
	ds_read_b128 v[186:189], v0 offset:160
	v_mfma_f32_32x32x16_bf16 v[64:79], v[6:9], v[128:131], v[64:79]
	s_waitcnt lgkmcnt(2)
	v_mfma_f32_32x32x16_bf16 v[80:95], v[10:13], v[128:131], v[80:95]
	s_waitcnt lgkmcnt(1)
	v_mfma_f32_32x32x16_bf16 v[64:79], v[2:5], v[112:115], v[64:79]
	ds_read_b128 v[2:5], v0 offset:6784
	ds_read_b128 v[132:135], v0 offset:6816
	v_add_u32_e32 v0, s28, v182
	ds_read_b64_tr_b16 v[144:145], v0 offset:0
	ds_read_b64_tr_b16 v[146:147], v0 offset:0x600
	ds_read_b64_tr_b16 v[136:137], v0 offset:0xc00
	ds_read_b64_tr_b16 v[138:139], v0 offset:0x1200
	ds_read_b64_tr_b16 v[10:11], v0 offset:0x1800
	s_waitcnt lgkmcnt(1)
	v_mfma_f32_32x32x16_bf16 v[80:95], v[2:5], v[112:115], v[80:95]
	ds_read_b64_tr_b16 v[12:13], v0 offset:0x1e00
	ds_read_b64_tr_b16 v[6:7], v0 offset:0x2400
	ds_read_b64_tr_b16 v[8:9], v0 offset:0x2a00
	ds_read_b64_tr_b16 v[148:149], v0 offset:64
	ds_read_b64_tr_b16 v[150:151], v0 offset:0x640
	ds_read_b64_tr_b16 v[140:141], v0 offset:0xc40
	ds_read_b64_tr_b16 v[142:143], v0 offset:0x1240
	s_waitcnt lgkmcnt(0)
	v_mfma_f32_32x32x16_bf16 v[80:95], v[132:135], v[108:111], v[80:95]
	ds_read_b64_tr_b16 v[132:133], v0 offset:0x1840
	ds_read_b64_tr_b16 v[134:135], v0 offset:0x1e40
	ds_read_b64_tr_b16 v[2:3], v0 offset:0x2440
	ds_read_b64_tr_b16 v[4:5], v0 offset:0x2a40
	v_mfma_f32_32x32x16_bf16 v[64:79], v[186:189], v[108:111], v[64:79]
	s_nop 10
	v_max3_f32 v0, v80, v81, v82
	v_max3_f32 v14, v64, v65, v66
	v_max3_f32 v0, v0, v83, v84
	v_max3_f32 v14, v14, v67, v68
	v_max3_f32 v0, v0, v85, v86
	v_max3_f32 v14, v14, v69, v70
	v_max3_f32 v0, v0, v87, v88
	v_max3_f32 v14, v14, v71, v72
	v_max3_f32 v0, v0, v89, v90
	v_max3_f32 v14, v14, v73, v74
	v_max3_f32 v0, v0, v91, v92
	v_max3_f32 v14, v14, v75, v76
	v_max3_f32 v0, v0, v93, v94
	v_max3_f32 v14, v14, v77, v78
	v_max3_f32 v0, v0, v95, v79
	v_max_f32_e32 v0, v0, v14
	v_mov_b32_e32 v14, v0
	s_nop 1
	v_permlane32_swap_b32_e32 v0, v14
	v_max_f32_e32 v14, v0, v14
	s_cbranch_scc0 .LBB0_1091
	v_cmp_lt_f32_e32 vcc, s60, v14
	s_mov_b64 s[54:55], 0
	s_mov_b64 s[52:53], 0
	s_cbranch_vccnz .Lmla_rare_0

; DI void mla_unit(const Params& p, char* lds, int seqbase, int S, int h, int qb) {
;     ...
;     if (kt == 0 || __any(pmax > 8.f)) {
;       const float delta = kt == 0 ? pmax : fmaxf(pmax, 0.f);
;       const float alpha = kt == 0 ? 1.f : __builtin_amdgcn_exp2f(-delta);
.Lmla_rare_0:
	v_max_f32_e32 v0, v14, v14
	v_max_f32_e32 v0, 0, v0
	s_mov_b64 s[52:53], -1

; DI void mla_unit(const Params& p, char* lds, int seqbase, int S, int h, int qb) {
;     ...
;     if (kt == 0 || __any(pmax > 8.f)) {
;       const float delta = kt == 0 ? pmax : fmaxf(pmax, 0.f);
;       const float alpha = kt == 0 ? 1.f : __builtin_amdgcn_exp2f(-delta);
; #pragma unroll
;       for (int r = 0; r < 16; ++r) { negm[r] -= delta; p0[r] -= delta; p1[r] -= delta; o0[r] *= alpha; o1[r] *= alpha; }
;       l_run *= alpha;
;     }
.LBB0_1086:
	s_andn2_b64 vcc, exec, s[52:53]
	s_cbranch_vccnz .LBB0_1088
	v_exp_f32_e64 v14, -v0
	v_pk_add_f32 v[64:65], v[64:65], v[0:1] op_sel_hi:[1,0] neg_lo:[0,1] neg_hi:[0,1]
	v_pk_add_f32 v[80:81], v[80:81], v[0:1] op_sel_hi:[1,0] neg_lo:[0,1] neg_hi:[0,1]
	v_pk_add_f32 v[66:67], v[66:67], v[0:1] op_sel_hi:[1,0] neg_lo:[0,1] neg_hi:[0,1]
	v_cndmask_b32_e64 v14, v14, 1.0, s[50:51]
	v_pk_add_f32 v[82:83], v[82:83], v[0:1] op_sel_hi:[1,0] neg_lo:[0,1] neg_hi:[0,1]
	v_pk_add_f32 v[68:69], v[68:69], v[0:1] op_sel_hi:[1,0] neg_lo:[0,1] neg_hi:[0,1]
	v_pk_add_f32 v[84:85], v[84:85], v[0:1] op_sel_hi:[1,0] neg_lo:[0,1] neg_hi:[0,1]
	v_pk_add_f32 v[70:71], v[70:71], v[0:1] op_sel_hi:[1,0] neg_lo:[0,1] neg_hi:[0,1]
	v_pk_add_f32 v[86:87], v[86:87], v[0:1] op_sel_hi:[1,0] neg_lo:[0,1] neg_hi:[0,1]
	v_pk_add_f32 v[72:73], v[72:73], v[0:1] op_sel_hi:[1,0] neg_lo:[0,1] neg_hi:[0,1]
	v_pk_add_f32 v[88:89], v[88:89], v[0:1] op_sel_hi:[1,0] neg_lo:[0,1] neg_hi:[0,1]
	v_pk_add_f32 v[74:75], v[74:75], v[0:1] op_sel_hi:[1,0] neg_lo:[0,1] neg_hi:[0,1]
	v_pk_add_f32 v[90:91], v[90:91], v[0:1] op_sel_hi:[1,0] neg_lo:[0,1] neg_hi:[0,1]
	v_pk_add_f32 v[76:77], v[76:77], v[0:1] op_sel_hi:[1,0] neg_lo:[0,1] neg_hi:[0,1]
	v_pk_add_f32 v[92:93], v[92:93], v[0:1] op_sel_hi:[1,0] neg_lo:[0,1] neg_hi:[0,1]
	v_sub_f32_e32 v63, v63, v0
	v_sub_f32_e32 v62, v62, v0
	v_sub_f32_e32 v61, v61, v0
	v_sub_f32_e32 v60, v60, v0
	v_sub_f32_e32 v59, v59, v0
	v_sub_f32_e32 v58, v58, v0
	v_sub_f32_e32 v57, v57, v0
	v_sub_f32_e32 v56, v56, v0
	v_sub_f32_e32 v55, v55, v0
	v_sub_f32_e32 v54, v54, v0
	v_sub_f32_e32 v53, v53, v0
	v_sub_f32_e32 v52, v52, v0
	v_sub_f32_e32 v51, v51, v0
	v_sub_f32_e32 v50, v50, v0
	v_sub_f32_e32 v49, v49, v0
	v_sub_f32_e32 v48, v48, v0
	v_pk_add_f32 v[78:79], v[78:79], v[0:1] op_sel_hi:[1,0] neg_lo:[0,1] neg_hi:[0,1]
	v_pk_add_f32 v[94:95], v[94:95], v[0:1] op_sel_hi:[1,0] neg_lo:[0,1] neg_hi:[0,1]
	v_pk_mul_f32 v[46:47], v[46:47], v[14:15] op_sel_hi:[1,0]
	v_pk_mul_f32 v[44:45], v[44:45], v[14:15] op_sel_hi:[1,0]
	v_pk_mul_f32 v[42:43], v[42:43], v[14:15] op_sel_hi:[1,0]
	v_pk_mul_f32 v[40:41], v[40:41], v[14:15] op_sel_hi:[1,0]
	v_pk_mul_f32 v[38:39], v[38:39], v[14:15] op_sel_hi:[1,0]
	v_pk_mul_f32 v[36:37], v[36:37], v[14:15] op_sel_hi:[1,0]
	v_pk_mul_f32 v[34:35], v[34:35], v[14:15] op_sel_hi:[1,0]
	v_pk_mul_f32 v[32:33], v[32:33], v[14:15] op_sel_hi:[1,0]
	v_pk_mul_f32 v[30:31], v[30:31], v[14:15] op_sel_hi:[1,0]
	v_pk_mul_f32 v[28:29], v[28:29], v[14:15] op_sel_hi:[1,0]
	v_pk_mul_f32 v[26:27], v[26:27], v[14:15] op_sel_hi:[1,0]
	v_pk_mul_f32 v[24:25], v[24:25], v[14:15] op_sel_hi:[1,0]
	v_pk_mul_f32 v[22:23], v[22:23], v[14:15] op_sel_hi:[1,0]
	v_pk_mul_f32 v[20:21], v[20:21], v[14:15] op_sel_hi:[1,0]
	v_pk_mul_f32 v[18:19], v[18:19], v[14:15] op_sel_hi:[1,0]
	v_pk_mul_f32 v[16:17], v[16:17], v[14:15] op_sel_hi:[1,0]
	v_mul_f32_e32 v153, v153, v14
	s_branch .LBB0_1088

; #define MFMA32(a, b, c) __builtin_amdgcn_mfma_f32_32x32x16_bf16((a), (b), (c), 0, 0, 0)
; DI float pl32_max(float v) { auto rr = __builtin_amdgcn_permlane32_swap(__float_as_uint(v), __float_as_uint(v), false, false); return fmaxf(__uint_as_float(rr[0]), __uint_as_float(rr[1])); }
; template <int OFF> DI s16x4 tr_read_o(unsigned addr) { s16x4 r; asm volatile("ds_read_b64_tr_b16 %0, %1 offset:%2" : "=&v"(r) : "v"(addr), "i"(OFF) : "memory"); return r; }
; DI float max_nn(float a, float b) { return __builtin_amdgcn_fmed3f(a, b, __builtin_inff()); }
; DI void mla_unit(const Params& p, char* lds, int seqbase, int S, int h, int qb) {
;     ...
;     const u16* kl = Kl + cur * 64 * KP + r32 * KP + 8 * hi;
;     f32x16 p0, p1;
;     { const bf16x8 k0 = *(const bf16x8*)(kl), k1 = *(const bf16x8*)(kl + 32 * KP);
;       p0 = MFMA32(k0, qf[0], negm); p1 = MFMA32(k1, qf[0], negm); }
; #pragma unroll
;     for (int d0 = 1; d0 < 6; ++d0) {
;       const bf16x8 k0 = *(const bf16x8*)(kl + d0 * 16), k1 = *(const bf16x8*)(kl + 32 * KP + d0 * 16);
;       p0 = MFMA32(k0, qf[d0], p0); p1 = MFMA32(k1, qf[d0], p1);
;     }
;     const unsigned tb = trb + cur * (64 * VP * 2);
;     constexpr int R8 = 8 * VP * 2;
;     const s16x4 a0 = tr_read_o<0>(tb), b0 = tr_read_o<R8>(tb), a1 = tr_read_o<2 * R8>(tb), b1 = tr_read_o<3 * R8>(tb);
;     const s16x4 a2 = tr_read_o<4 * R8>(tb), b2 = tr_read_o<5 * R8>(tb), a3 = tr_read_o<6 * R8>(tb), b3 = tr_read_o<7 * R8>(tb);
;     const s16x4 c0 = tr_read_o<64>(tb), d0_ = tr_read_o<R8 + 64>(tb), c1 = tr_read_o<2 * R8 + 64>(tb), d1 = tr_read_o<3 * R8 + 64>(tb);
;     const s16x4 c2 = tr_read_o<4 * R8 + 64>(tb), d2 = tr_read_o<5 * R8 + 64>(tb), c3 = tr_read_o<6 * R8 + 64>(tb), d3 = tr_read_o<7 * R8 + 64>(tb);
;     float pmax = max_nn(p0[0], p1[0]);
; #pragma unroll
;     for (int r = 1; r < 16; ++r) pmax = max_nn(pmax, max_nn(p0[r], p1[r]));
;     pmax = pl32_max(pmax);
;     if (kt == 0 || __any(pmax > 8.f)) {
;       const float delta = kt == 0 ? pmax : fmaxf(pmax, 0.f);
;       const float alpha = kt == 0 ? 1.f : __builtin_amdgcn_exp2f(-delta);
; #pragma unroll
;       for (int r = 0; r < 16; ++r) { negm[r] -= delta; p0[r] -= delta; p1[r] -= delta; o0[r] *= alpha; o1[r] *= alpha; }
;       l_run *= alpha;
;     }
.LBB0_1111:
	s_mul_i32 s28, s18, 0x3400
	v_add_u32_e32 v2, s28, v181
	ds_read_b128 v[4:7], v2
	ds_read_b128 v[8:11], v2 offset:32
	s_mul_i32 s28, s18, 0x3000
	s_cmp_eq_u32 s38, 0
	s_cselect_b64 s[46:47], -1, 0
	s_waitcnt lgkmcnt(1)
	v_mfma_f32_32x32x16_bf16 v[66:81], v[4:7], v[118:121], v[50:65]
	ds_read_b128 v[4:7], v2 offset:6656
	ds_read_b128 v[12:15], v2 offset:6688
	s_cmp_lg_u32 s38, 0
	s_waitcnt lgkmcnt(1)
	v_mfma_f32_32x32x16_bf16 v[82:97], v[4:7], v[118:121], v[50:65]
	v_mfma_f32_32x32x16_bf16 v[66:81], v[8:11], v[122:125], v[66:81]
	ds_read_b128 v[4:7], v2 offset:64
	ds_read_b128 v[8:11], v2 offset:96
	s_waitcnt lgkmcnt(2)
	v_mfma_f32_32x32x16_bf16 v[82:97], v[12:15], v[122:125], v[82:97]
	s_waitcnt lgkmcnt(1)
	v_mfma_f32_32x32x16_bf16 v[66:81], v[4:7], v[126:129], v[66:81]
	ds_read_b128 v[4:7], v2 offset:6720
	ds_read_b128 v[12:15], v2 offset:6752
	s_waitcnt lgkmcnt(1)
	v_mfma_f32_32x32x16_bf16 v[82:97], v[4:7], v[126:129], v[82:97]
	ds_read_b128 v[4:7], v2 offset:128
	ds_read_b128 v[188:191], v2 offset:160
	v_mfma_f32_32x32x16_bf16 v[66:81], v[8:11], v[130:133], v[66:81]
	s_waitcnt lgkmcnt(2)
	v_mfma_f32_32x32x16_bf16 v[82:97], v[12:15], v[130:133], v[82:97]
	s_waitcnt lgkmcnt(1)
	v_mfma_f32_32x32x16_bf16 v[66:81], v[4:7], v[114:117], v[66:81]
	ds_read_b128 v[4:7], v2 offset:6784
	ds_read_b128 v[134:137], v2 offset:6816
	v_add_u32_e32 v2, s28, v182
	ds_read_b64_tr_b16 v[146:147], v2 offset:0
	ds_read_b64_tr_b16 v[148:149], v2 offset:0x600
	ds_read_b64_tr_b16 v[138:139], v2 offset:0xc00
	ds_read_b64_tr_b16 v[140:141], v2 offset:0x1200
	ds_read_b64_tr_b16 v[12:13], v2 offset:0x1800
	s_waitcnt lgkmcnt(1)
	v_mfma_f32_32x32x16_bf16 v[82:97], v[4:7], v[114:117], v[82:97]
	ds_read_b64_tr_b16 v[14:15], v2 offset:0x1e00
	ds_read_b64_tr_b16 v[8:9], v2 offset:0x2400
	ds_read_b64_tr_b16 v[10:11], v2 offset:0x2a00
	ds_read_b64_tr_b16 v[150:151], v2 offset:64
	ds_read_b64_tr_b16 v[152:153], v2 offset:0x640
	ds_read_b64_tr_b16 v[142:143], v2 offset:0xc40
	ds_read_b64_tr_b16 v[144:145], v2 offset:0x1240
	s_waitcnt lgkmcnt(0)
	v_mfma_f32_32x32x16_bf16 v[82:97], v[134:137], v[110:113], v[82:97]
	ds_read_b64_tr_b16 v[134:135], v2 offset:0x1840
	ds_read_b64_tr_b16 v[136:137], v2 offset:0x1e40
	ds_read_b64_tr_b16 v[4:5], v2 offset:0x2440
	ds_read_b64_tr_b16 v[6:7], v2 offset:0x2a40
	v_mfma_f32_32x32x16_bf16 v[66:81], v[188:191], v[110:113], v[66:81]
	s_nop 10
	v_max3_f32 v2, v82, v83, v84
	v_max3_f32 v16, v66, v67, v68
	v_max3_f32 v2, v2, v85, v86
	v_max3_f32 v16, v16, v69, v70
	v_max3_f32 v2, v2, v87, v88
	v_max3_f32 v16, v16, v71, v72
	v_max3_f32 v2, v2, v89, v90
	v_max3_f32 v16, v16, v73, v74
	v_max3_f32 v2, v2, v91, v92
	v_max3_f32 v16, v16, v75, v76
	v_max3_f32 v2, v2, v93, v94
	v_max3_f32 v16, v16, v77, v78
	v_max3_f32 v2, v2, v95, v96
	v_max3_f32 v16, v16, v79, v80
	v_max3_f32 v2, v2, v97, v81
	v_max_f32_e32 v2, v2, v16
	v_mov_b32_e32 v16, v2
	s_nop 1
	v_permlane32_swap_b32_e32 v2, v16
	v_max_f32_e32 v16, v2, v16
	s_cbranch_scc0 .LBB0_1121
	v_cmp_lt_f32_e32 vcc, s21, v16
	s_mov_b64 s[50:51], 0
	s_mov_b64 s[48:49], 0
	s_cbranch_vccnz .Lmla_rare_1

; DI void mla_unit(const Params& p, char* lds, int seqbase, int S, int h, int qb) {
;     ...
;     if (kt == 0 || __any(pmax > 8.f)) {
;       const float delta = kt == 0 ? pmax : fmaxf(pmax, 0.f);
;       const float alpha = kt == 0 ? 1.f : __builtin_amdgcn_exp2f(-delta);
.Lmla_rare_1:
	v_max_f32_e32 v2, v16, v16
	v_max_f32_e32 v2, 0, v2
	s_mov_b64 s[48:49], -1

; DI void mla_unit(const Params& p, char* lds, int seqbase, int S, int h, int qb) {
;     ...
;     if (kt == 0 || __any(pmax > 8.f)) {
;       const float delta = kt == 0 ? pmax : fmaxf(pmax, 0.f);
;       const float alpha = kt == 0 ? 1.f : __builtin_amdgcn_exp2f(-delta);
; #pragma unroll
;       for (int r = 0; r < 16; ++r) { negm[r] -= delta; p0[r] -= delta; p1[r] -= delta; o0[r] *= alpha; o1[r] *= alpha; }
;       l_run *= alpha;
;     }
.LBB0_1116:
	s_andn2_b64 vcc, exec, s[48:49]
	s_cbranch_vccnz .LBB0_1118
	v_exp_f32_e64 v16, -v2
	v_pk_add_f32 v[66:67], v[66:67], v[2:3] op_sel_hi:[1,0] neg_lo:[0,1] neg_hi:[0,1]
	v_pk_add_f32 v[82:83], v[82:83], v[2:3] op_sel_hi:[1,0] neg_lo:[0,1] neg_hi:[0,1]
	v_pk_add_f32 v[68:69], v[68:69], v[2:3] op_sel_hi:[1,0] neg_lo:[0,1] neg_hi:[0,1]
	v_cndmask_b32_e64 v16, v16, 1.0, s[46:47]
	v_pk_add_f32 v[84:85], v[84:85], v[2:3] op_sel_hi:[1,0] neg_lo:[0,1] neg_hi:[0,1]
	v_pk_add_f32 v[70:71], v[70:71], v[2:3] op_sel_hi:[1,0] neg_lo:[0,1] neg_hi:[0,1]
	v_pk_add_f32 v[86:87], v[86:87], v[2:3] op_sel_hi:[1,0] neg_lo:[0,1] neg_hi:[0,1]
	v_pk_add_f32 v[72:73], v[72:73], v[2:3] op_sel_hi:[1,0] neg_lo:[0,1] neg_hi:[0,1]
	v_pk_add_f32 v[88:89], v[88:89], v[2:3] op_sel_hi:[1,0] neg_lo:[0,1] neg_hi:[0,1]
	v_pk_add_f32 v[74:75], v[74:75], v[2:3] op_sel_hi:[1,0] neg_lo:[0,1] neg_hi:[0,1]
	v_pk_add_f32 v[90:91], v[90:91], v[2:3] op_sel_hi:[1,0] neg_lo:[0,1] neg_hi:[0,1]
	v_pk_add_f32 v[76:77], v[76:77], v[2:3] op_sel_hi:[1,0] neg_lo:[0,1] neg_hi:[0,1]
	v_pk_add_f32 v[92:93], v[92:93], v[2:3] op_sel_hi:[1,0] neg_lo:[0,1] neg_hi:[0,1]
	v_pk_add_f32 v[78:79], v[78:79], v[2:3] op_sel_hi:[1,0] neg_lo:[0,1] neg_hi:[0,1]
	v_pk_add_f32 v[94:95], v[94:95], v[2:3] op_sel_hi:[1,0] neg_lo:[0,1] neg_hi:[0,1]
	v_sub_f32_e32 v65, v65, v2
	v_sub_f32_e32 v64, v64, v2
	v_sub_f32_e32 v63, v63, v2
	v_sub_f32_e32 v62, v62, v2
	v_sub_f32_e32 v61, v61, v2
	v_sub_f32_e32 v60, v60, v2
	v_sub_f32_e32 v59, v59, v2
	v_sub_f32_e32 v58, v58, v2
	v_sub_f32_e32 v57, v57, v2
	v_sub_f32_e32 v56, v56, v2
	v_sub_f32_e32 v55, v55, v2
	v_sub_f32_e32 v54, v54, v2
	v_sub_f32_e32 v53, v53, v2
	v_sub_f32_e32 v52, v52, v2
	v_sub_f32_e32 v51, v51, v2
	v_sub_f32_e32 v50, v50, v2
	v_pk_add_f32 v[80:81], v[80:81], v[2:3] op_sel_hi:[1,0] neg_lo:[0,1] neg_hi:[0,1]
	v_pk_add_f32 v[96:97], v[96:97], v[2:3] op_sel_hi:[1,0] neg_lo:[0,1] neg_hi:[0,1]
	v_pk_mul_f32 v[48:49], v[48:49], v[16:17] op_sel_hi:[1,0]
	v_pk_mul_f32 v[46:47], v[46:47], v[16:17] op_sel_hi:[1,0]
	v_pk_mul_f32 v[44:45], v[44:45], v[16:17] op_sel_hi:[1,0]
	v_pk_mul_f32 v[42:43], v[42:43], v[16:17] op_sel_hi:[1,0]
	v_pk_mul_f32 v[40:41], v[40:41], v[16:17] op_sel_hi:[1,0]
	v_pk_mul_f32 v[38:39], v[38:39], v[16:17] op_sel_hi:[1,0]
	v_pk_mul_f32 v[36:37], v[36:37], v[16:17] op_sel_hi:[1,0]
	v_pk_mul_f32 v[34:35], v[34:35], v[16:17] op_sel_hi:[1,0]
	v_pk_mul_f32 v[32:33], v[32:33], v[16:17] op_sel_hi:[1,0]
	v_pk_mul_f32 v[30:31], v[30:31], v[16:17] op_sel_hi:[1,0]
	v_pk_mul_f32 v[28:29], v[28:29], v[16:17] op_sel_hi:[1,0]
	v_pk_mul_f32 v[26:27], v[26:27], v[16:17] op_sel_hi:[1,0]
	v_pk_mul_f32 v[24:25], v[24:25], v[16:17] op_sel_hi:[1,0]
	v_pk_mul_f32 v[22:23], v[22:23], v[16:17] op_sel_hi:[1,0]
	v_pk_mul_f32 v[20:21], v[20:21], v[16:17] op_sel_hi:[1,0]
	v_pk_mul_f32 v[18:19], v[18:19], v[16:17] op_sel_hi:[1,0]
	v_mul_f32_e32 v1, v1, v16
	s_branch .LBB0_1118
